# v43
# speedup vs baseline: 1.0335x; 1.0013x over previous
; #define SBAR() __builtin_amdgcn_sched_barrier(0)
; __device__ __forceinline__ int v_st(int k, int c) { const int kk = (k & ~0xC) | ((k & 4) << 1) | ((k & 8) >> 1); return ((kk >> 3) * 4 + (c >> 5)) * 512 + ((kk & 7) * 32 + (c & 31)) * 2; }
; __device__ __forceinline__ int v_rd_base(int lane) { return ((lane & 3) << 3) | (((lane >> 2) & 3) << 6) | (((lane >> 4) & 1) << 5) | (((lane >> 5) & 1) << 8); }
; #define VMW() asm volatile("s_waitcnt vmcnt(0)" ::: "memory")
; #define SLOAD_H(Kp, Vp, k0) do { S.st_v0 = load8<TIn>(ROW(Vp, k0, sr)); S.st_v1 = load8<TIn>(ROW(Vp, k0, 32 + sr));              \
;                          S.st_k0 = load8<TIn>(ROW(Kp, k0, sr)); S.st_k1 = load8<TIn>(ROW(Kp, k0, 32 + sr)); } while (0)
; #define SWRITE_HV(bf) do { *(bf16x8*)(V_lds + (bf) * SHM_V + vst0) = S.st_v0; *(bf16x8*)(V_lds + (bf) * SHM_V + vst1) = S.st_v1; } while (0)
; #define SWRITE_H(bf) do { SWRITE_HV(bf); SWRITE_HK(bf); } while (0)
; #define SLOAD_F(p, k0) do { S.sf0 = *(const f32x4*)ROW(p, k0, sr); S.sf1 = *(const f32x4*)(ROW(p, k0, sr) + 4);                \
;                             S.sf2 = *(const f32x4*)ROW(p, k0, 32 + sr); S.sf3 = *(const f32x4*)(ROW(p, k0, 32 + sr) + 4); } while (0)
; #define ACT(t) (KBASE(t) <= qlo + QBLK - 1 && KBASE(t) + KVBLK - 1 >= qlo - W + 1)
; template <class TIn, class TOut>
; __device__ __forceinline__ void causal_swa_block(const BlockRef<TIn, TOut>& cur, const BlockRef<TIn, TOut>& nxt, int skv, int W, char* lds, Seam<TIn>& S) {
;     ...
;     float m_reg = -1e30f, l_reg = 0; f32x16 o[4] = {};
;     const int sr = tid >> 4, sc = (tid & 15) * 8, vst0 = v_st(sr, sc), vst1 = v_st(32 + sr, sc), kws = KSWZ(sr, sc * 2);
;     const int vb0 = (int)(uintptr_t)V_lds + v_rd_base(lane);
;     ...
;     if constexpr (F32) { VMW(); SWRITE_VF(0); SBAR(); } else { SWRITE_HV(0); SBAR(); }
;     if (NT > 1) { if constexpr (F32) SLOAD_F((const float*)Kh, KBASE(1)); else SLOAD_H(Kh, Vh, KBASE(1)); }
;     SBAR(); qkt<0, SK>(pA0, pA1, K_lds, r32, hi, S.qr, ACT(0));
;     if constexpr (F32) { if (NT > 1) { VMW(); SWRITE_KF(1); SBAR(); SLOAD_F((const float*)Vh, KBASE(1)); } }
;     MASKT(pA0, pA1, 0); partialSM(pA0, pA1, m_reg, mnA, alA);
;     if (NT > 1) { VMW(); if constexpr (F32) { SWRITE_VF(1); SBAR(); if (NT > 2) SLOAD_F((const float*)Kh, KBASE(2)); } else SWRITE_H(1); }
;     __syncthreads();
.LBB0_204:
	s_and_b32 s42, s42, 0x3fffffc0
	v_and_b32_e32 v49, 63, v171
	s_lshl_b32 s42, s42, 2
	s_lshr_b32 s71, s71, 6
	s_add_i32 s42, s42, 0
	v_lshlrev_b32_e32 v50, 8, v160
	v_and_b32_e32 v51, 0x70, v171
	v_lshlrev_b32_e32 v52, 4, v49
	s_add_i32 s71, s71, 4
	s_add_i32 s42, s42, 0x10000
	v_bitop3_b32 v51, v200, v50, v51 bitop3:0xde
	v_lshlrev_b32_e32 v50, 3, v49
	v_and_b32_e32 v52, 0xc0, v52
	v_lshlrev_b32_e32 v53, 1, v49
	v_and_or_b32 v52, v50, 24, v52
	v_and_b32_e32 v53, 32, v53
	v_and_b32_e32 v50, 0x100, v50
	s_cmp_lg_u32 0, -1
	v_or3_b32 v50, v52, v53, v50
	s_cselect_b32 s43, 0, 0
	v_add_u32_e32 v173, s43, v50
	v_max_f32_e32 v50, v17, v17
	v_max_f32_e32 v52, v16, v16
	v_max_f32_e32 v50, v52, v50
	v_max3_f32 v50, v50, v18, v19
	v_max3_f32 v50, v50, v20, v21
	v_max3_f32 v50, v50, v22, v23
	v_max3_f32 v50, v50, v24, v25
	v_max3_f32 v50, v50, v26, v27
	v_max3_f32 v50, v50, v28, v29
	v_max3_f32 v50, v50, v30, v31
	v_max3_f32 v50, v50, v0, v1
	v_max3_f32 v50, v50, v2, v3
	v_max3_f32 v50, v50, v4, v5
	v_max3_f32 v50, v50, v6, v7
	v_max3_f32 v50, v50, v8, v9
	v_max3_f32 v50, v50, v10, v11
	v_max3_f32 v50, v50, v12, v13
	v_max3_f32 v50, v50, v14, v15
	v_mov_b32_e32 v52, v50
	s_nop 1
	v_permlane32_swap_b32_e32 v50, v52
	v_max_f32_e32 v52, v52, v52
	v_max_f32_e32 v50, v50, v50
	v_max_f32_e32 v50, v50, v52
	v_add_f32_e32 v52, 0x7149f2ca, v50
	v_mul_f32_e32 v52, 0x3db504f3, v52
	v_max_f32_e32 v50, 0xf149f2ca, v50
	v_cmp_ge_f32_e32 vcc, s66, v52
	v_sub_f32_e32 v52, 0xf149f2ca, v50
	s_add_i32 s72, s70, 0xffffe01f
	v_mul_f32_e32 v52, 0x3e0293ee, v52
	v_exp_f32_e32 v52, v52
	s_cmp_eq_u64 vcc, exec
	s_cselect_b64 vcc, -1, 0
	v_cndmask_b32_e32 v184, v50, v236, vcc
	v_mul_f32_e32 v50, 0xbe0293ee, v184
	v_cndmask_b32_e64 v183, v52, 1.0, vcc
	v_mov_b32_e32 v52, v50
	v_fmamk_f32 v16, v16, 0x3e0293ee, v50
	v_fmamk_f32 v17, v17, 0x3e0293ee, v50
	v_fmamk_f32 v18, v18, 0x3e0293ee, v50
	v_fmamk_f32 v19, v19, 0x3e0293ee, v50
	v_fmamk_f32 v20, v20, 0x3e0293ee, v50
	v_fmamk_f32 v21, v21, 0x3e0293ee, v50
	v_fmamk_f32 v22, v22, 0x3e0293ee, v50
	v_fmamk_f32 v23, v23, 0x3e0293ee, v50
	v_fmamk_f32 v24, v24, 0x3e0293ee, v50
	v_fmamk_f32 v25, v25, 0x3e0293ee, v50
	v_fmamk_f32 v26, v26, 0x3e0293ee, v50
	v_fmamk_f32 v27, v27, 0x3e0293ee, v50
	v_fmamk_f32 v28, v28, 0x3e0293ee, v50
	v_fmamk_f32 v29, v29, 0x3e0293ee, v50
	v_fmamk_f32 v30, v30, 0x3e0293ee, v50
	v_fmac_f32_e32 v52, 0x3e0293ee, v31
	v_exp_f32_e32 v198, v16
	v_exp_f32_e32 v199, v17
	v_exp_f32_e32 v210, v18
	v_exp_f32_e32 v212, v19
	v_exp_f32_e32 v213, v20
	v_exp_f32_e32 v215, v21
	v_exp_f32_e32 v211, v22
	v_exp_f32_e32 v214, v23
	v_exp_f32_e32 v190, v24
	v_exp_f32_e32 v192, v25
	v_exp_f32_e32 v193, v26
	v_exp_f32_e32 v196, v27
	v_exp_f32_e32 v191, v28
	v_exp_f32_e32 v194, v29
	v_exp_f32_e32 v195, v30
	v_exp_f32_e32 v197, v52
	v_add_u32_e32 v176, 0, v51
	v_lshl_add_u64 v[168:169], s[8:9], 0, v[200:201]
	s_add_i32 s8, s70, 0xffffdf45
	v_pk_fma_f32 v[156:157], v[0:1], s[34:35], v[50:51] op_sel_hi:[1,0,0]
	s_waitcnt vmcnt(0)
	s_waitcnt vmcnt(3)
	ds_write_b128 v181, v[32:35] offset:16384
	s_waitcnt vmcnt(2)
	ds_write_b128 v182, v[36:39] offset:16384
	s_waitcnt vmcnt(1)
	ds_write_b128 v176, v[40:43] offset:49152
	s_waitcnt vmcnt(0)
	ds_write_b128 v176, v[44:47] offset:57344
	v_add_u32_e32 v0, s8, v172
	v_mov_b32_e32 v32, v201
	v_mov_b32_e32 v33, v201
	v_mov_b32_e32 v46, v201
	v_mov_b32_e32 v47, v201
	v_pk_fma_f32 v[146:147], v[14:15], s[34:35], v[50:51] op_sel_hi:[1,0,0]
	v_pk_fma_f32 v[152:153], v[12:13], s[34:35], v[50:51] op_sel_hi:[1,0,0]
	v_pk_fma_f32 v[158:159], v[10:11], s[34:35], v[50:51] op_sel_hi:[1,0,0]
	v_pk_fma_f32 v[144:145], v[8:9], s[34:35], v[50:51] op_sel_hi:[1,0,0]
	v_pk_fma_f32 v[148:149], v[6:7], s[34:35], v[50:51] op_sel_hi:[1,0,0]
	v_pk_fma_f32 v[150:151], v[4:5], s[34:35], v[50:51] op_sel_hi:[1,0,0]
	v_pk_fma_f32 v[154:155], v[2:3], s[34:35], v[50:51] op_sel_hi:[1,0,0]
	v_lshl_add_u64 v[166:167], s[40:41], 0, v[200:201]
	v_cmp_gt_u32_e64 s[40:41], 32, v49
	v_lshl_add_u32 v174, v48, 2, s42
	v_sub_u32_e32 v185, v0, v48
	v_mov_b32_e32 v34, v201
	v_mov_b32_e32 v35, v201
	v_mov_b32_e32 v36, v201
	v_mov_b32_e32 v37, v201
	v_mov_b32_e32 v38, v201
	v_mov_b32_e32 v39, v201
	v_mov_b32_e32 v40, v201
	v_mov_b32_e32 v41, v201
	v_mov_b32_e32 v42, v201
	v_mov_b32_e32 v43, v201
	v_mov_b32_e32 v44, v201
	v_mov_b32_e32 v45, v201
	v_mov_b64_e32 v[62:63], v[46:47]
	v_mov_b64_e32 v[16:17], v[32:33]
	v_mov_b64_e32 v[0:1], v[32:33]
	s_mov_b32 s73, 2
	v_lshl_add_u32 v175, v172, 2, s42
	v_mov_b32_e32 v177, 0
	s_movk_i32 s74, 0x7f
	v_mov_b64_e32 v[60:61], v[44:45]
	v_mov_b64_e32 v[58:59], v[42:43]
	v_mov_b64_e32 v[56:57], v[40:41]
	v_mov_b64_e32 v[54:55], v[38:39]
	v_mov_b64_e32 v[52:53], v[36:37]
	v_mov_b64_e32 v[50:51], v[34:35]
	v_mov_b64_e32 v[48:49], v[32:33]
	v_mov_b64_e32 v[18:19], v[34:35]
	v_mov_b64_e32 v[20:21], v[36:37]
	v_mov_b64_e32 v[22:23], v[38:39]
	v_mov_b64_e32 v[24:25], v[40:41]
	v_mov_b64_e32 v[26:27], v[42:43]
	v_mov_b64_e32 v[28:29], v[44:45]
	v_mov_b64_e32 v[30:31], v[46:47]
	v_mov_b64_e32 v[2:3], v[34:35]
	v_mov_b64_e32 v[4:5], v[36:37]
	v_mov_b64_e32 v[6:7], v[38:39]
	v_mov_b64_e32 v[8:9], v[40:41]
	v_mov_b64_e32 v[10:11], v[42:43]
	v_mov_b64_e32 v[12:13], v[44:45]
	v_mov_b64_e32 v[14:15], v[46:47]
	s_waitcnt lgkmcnt(0)
	s_barrier
	v_readfirstlane_b32 s98, v168
	v_readfirstlane_b32 s99, v169
	v_readfirstlane_b32 s100, v166
	v_readfirstlane_b32 s101, v167
	s_nop 4
	s_add_i32 s82, s74, 1
	s_lshl_b32 s82, s82, 8
	s_add_u32 s78, s98, s82
	s_addc_u32 s79, s99, 0
	s_add_u32 s80, s78, 0x2000
	s_addc_u32 s81, s79, 0
	v_lshl_add_u32 v240, v160, 8, v200
	global_load_dwordx4 v[136:139], v240, s[78:79]
	global_load_dwordx4 v[140:143], v240, s[80:81]
; template <int KB, bool SK>
; __device__ __forceinline__ void qkt(f32x16& p0, f32x16& p1, const char* K_lds, int r32, int hi, const bf16x8* qr, bool act) {
;     if (SK && !act) { const float NEG = -__builtin_inff();
; #pragma unroll
;         for (int r = 0; r < 16; ++r) { p0[r] = NEG; p1[r] = NEG; } return; }
;     p0 = f32x16{}; p1 = f32x16{};
;     const char* kb[4];
; #pragma unroll
;     for (int dd = 0; dd < 4; ++dd) kb[dd] = K_lds + KB * SHM_K + KSWZ(r32, (dd * 16 + hi * 8) * 2);
; #pragma unroll
;     for (int d0 = 0; d0 < 8; ++d0) { const char* a = kb[d0 & 3] + (d0 >> 2) * 128;
;         bf16x8 b0 = *reinterpret_cast<const bf16x8*>(a);
;         bf16x8 b1 = *reinterpret_cast<const bf16x8*>(a + 32 * 256);
;         p0 = __builtin_amdgcn_mfma_f32_32x32x16_bf16(b0, qr[d0], p0, 0, 0, 0);
;         p1 = __builtin_amdgcn_mfma_f32_32x32x16_bf16(b1, qr[d0], p1, 0, 0, 0); }
; }
.LBB0_205:
	s_add_i32 s82, s74, 1
	s_lshl_b32 s82, s82, 8
	s_add_u32 s78, s100, s82
	s_addc_u32 s79, s101, 0
	s_add_u32 s80, s78, 0x2000
	s_addc_u32 s81, s79, 0
	v_lshl_add_u32 v240, v160, 8, v200
	global_load_dwordx4 v[128:131], v240, s[78:79]
	global_load_dwordx4 v[132:135], v240, s[80:81]
	ds_read_b128 v[64:67], v180 offset:49152
	ds_read_b128 v[68:71], v180 offset:57344
	ds_read_b128 v[224:227], v179 offset:49152
	ds_read_b128 v[248:251], v179 offset:57344
	ds_read_b128 v[216:219], v165 offset:49152
	ds_read_b128 v[220:223], v165 offset:57344
	v_exp_f32_e32 v240, v144
	v_add_f32_e32 v144, 0, v198
	v_add_f32_e32 v144, v199, v144
	v_add_f32_e32 v144, v210, v144
	v_add_f32_e32 v144, v212, v144
	v_add_f32_e32 v144, v213, v144
	s_waitcnt lgkmcnt(5)
	v_mfma_f32_32x32x16_bf16 v[80:95], v[64:67], v[124:127], 0
	v_add_f32_e32 v144, v215, v144
	v_add_f32_e32 v144, v211, v144
	v_add_f32_e32 v144, v214, v144
	v_add_f32_e32 v144, v190, v144
	s_waitcnt lgkmcnt(4)
	v_mfma_f32_32x32x16_bf16 v[64:79], v[68:71], v[124:127], 0
	v_add_f32_e32 v144, v192, v144
	v_add_f32_e32 v144, v193, v144
	v_add_f32_e32 v144, v196, v144
	v_add_f32_e32 v144, v191, v144
	v_add_f32_e32 v144, v194, v144
	v_add_f32_e32 v144, v195, v144
	s_waitcnt lgkmcnt(3)
	v_mfma_f32_32x32x16_bf16 v[80:95], v[224:227], v[120:123], v[80:95]
	v_add_f32_e32 v144, v197, v144
	v_exp_f32_e32 v241, v145
	v_exp_f32_e32 v242, v158
	v_exp_f32_e32 v243, v159
	s_waitcnt lgkmcnt(2)
	v_mfma_f32_32x32x16_bf16 v[64:79], v[248:251], v[120:123], v[64:79]
	ds_read_b128 v[224:227], v163 offset:49152
	ds_read_b128 v[248:251], v163 offset:57344
	v_exp_f32_e32 v244, v152
	v_exp_f32_e32 v245, v153
	v_exp_f32_e32 v246, v146
	v_exp_f32_e32 v247, v147
	v_cvt_pk_bf16_f32 v145, v210, v212
	v_cvt_pk_bf16_f32 v146, v213, v215
	s_waitcnt lgkmcnt(3)
	v_mfma_f32_32x32x16_bf16 v[80:95], v[216:219], v[116:119], v[80:95]
	v_cvt_pk_bf16_f32 v147, v211, v214
	v_cvt_pk_bf16_f32 v158, v244, v245
	v_cvt_pk_bf16_f32 v159, v246, v247
	s_sub_i32 s8, s74, 63
	s_waitcnt lgkmcnt(2)
	v_mfma_f32_32x32x16_bf16 v[64:79], v[220:223], v[116:119], v[64:79]
	ds_read_b128 v[216:219], v180 offset:49280
	ds_read_b128 v[220:223], v180 offset:57472
	v_permlane32_swap_b32_e32 v145, v147
	v_exp_f32_e32 v228, v156
	v_exp_f32_e32 v229, v157
	v_exp_f32_e32 v252, v154
	v_exp_f32_e32 v253, v155
	v_add_f32_e32 v144, v228, v144
	s_waitcnt lgkmcnt(3)
	v_mfma_f32_32x32x16_bf16 v[80:95], v[224:227], v[112:115], v[80:95]
	v_add_f32_e32 v144, v229, v144
	v_add_f32_e32 v144, v252, v144
	v_add_f32_e32 v144, v253, v144
	v_cvt_pk_bf16_f32 v152, v228, v229
	s_waitcnt lgkmcnt(2)
	v_mfma_f32_32x32x16_bf16 v[64:79], v[248:251], v[112:115], v[64:79]
	ds_read_b128 v[224:227], v179 offset:49280
	ds_read_b128 v[248:251], v179 offset:57472
	v_cvt_pk_bf16_f32 v153, v252, v253
	v_exp_f32_e32 v228, v150
	v_exp_f32_e32 v229, v151
	v_exp_f32_e32 v252, v148
	v_exp_f32_e32 v253, v149
	v_add_f32_e32 v144, v228, v144
	s_waitcnt lgkmcnt(3)
	v_mfma_f32_32x32x16_bf16 v[80:95], v[216:219], v[108:111], v[80:95]
	v_add_f32_e32 v144, v229, v144
	v_add_f32_e32 v144, v252, v144
	v_add_f32_e32 v144, v253, v144
	v_cvt_pk_bf16_f32 v154, v228, v229
	s_waitcnt lgkmcnt(2)
	v_mfma_f32_32x32x16_bf16 v[64:79], v[220:223], v[108:111], v[64:79]
	ds_read_b128 v[216:219], v165 offset:49280
	ds_read_b128 v[220:223], v165 offset:57472
	v_cvt_pk_bf16_f32 v155, v252, v253
	v_add_f32_e32 v144, v240, v144
	v_add_f32_e32 v144, v241, v144
	v_add_f32_e32 v144, v242, v144
	v_add_f32_e32 v144, v243, v144
	v_add_f32_e32 v144, v244, v144
	s_waitcnt lgkmcnt(3)
	v_mfma_f32_32x32x16_bf16 v[80:95], v[224:227], v[104:107], v[80:95]
	v_add_f32_e32 v144, v245, v144
	v_add_f32_e32 v144, v246, v144
	v_add_f32_e32 v186, v247, v144
	v_mov_b32_e32 v187, v186
	s_waitcnt lgkmcnt(2)
	v_mfma_f32_32x32x16_bf16 v[64:79], v[248:251], v[104:107], v[64:79]
	ds_read_b128 v[224:227], v163 offset:49280
	ds_read_b128 v[248:251], v163 offset:57472
	s_nop 1
	v_permlane32_swap_b32_e32 v186, v187
	v_cvt_pk_bf16_f32 v144, v198, v199
	v_cvt_pk_bf16_f32 v148, v190, v192
	v_cvt_pk_bf16_f32 v149, v193, v196
	v_cvt_pk_bf16_f32 v150, v191, v194
	s_waitcnt lgkmcnt(3)
	v_mfma_f32_32x32x16_bf16 v[80:95], v[216:219], v[100:103], v[80:95]
	v_cvt_pk_bf16_f32 v151, v195, v197
	v_cvt_pk_bf16_f32 v156, v240, v241
	v_cvt_pk_bf16_f32 v157, v242, v243
	v_permlane32_swap_b32_e32 v144, v146
	s_waitcnt lgkmcnt(2)
	v_mfma_f32_32x32x16_bf16 v[64:79], v[220:223], v[100:103], v[64:79]
	v_permlane32_swap_b32_e32 v148, v150
	v_permlane32_swap_b32_e32 v149, v151
	v_permlane32_swap_b32_e32 v152, v154
	v_permlane32_swap_b32_e32 v153, v155
	v_permlane32_swap_b32_e32 v156, v158
	v_permlane32_swap_b32_e32 v157, v159
	s_waitcnt lgkmcnt(1)
	v_mfma_f32_32x32x16_bf16 v[80:95], v[224:227], v[96:99], v[80:95]
	s_waitcnt lgkmcnt(0)
	v_mfma_f32_32x32x16_bf16 v[64:79], v[248:251], v[96:99], v[64:79]
	s_cmp_le_i32 s74, s70
	s_cselect_b64 s[42:43], -1, 0
	s_cmp_gt_i32 s8, s72
	s_cselect_b64 s[8:9], -1, 0
	s_and_b64 s[8:9], s[42:43], s[8:9]
	s_and_b64 vcc, exec, s[8:9]
	s_cbranch_vccnz .Lmy_h1_pv
; __device__ __forceinline__ void mask_tile(f32x16& p0, f32x16& p1, int dq, unsigned W) {
;     const float NEG = -__builtin_inff();
; #pragma unroll
;     for (int r = 0; r < 16; ++r) {
;         const int c = (r & 3) + 8 * (r >> 2);
;         if ((unsigned)(dq - c) >= W) p0[r] = NEG;
;         if ((unsigned)(dq - c - 32) >= W) p1[r] = NEG;
;     }
; }
; template <int VB, bool SK>
; __device__ __forceinline__ void pv_tile(f32x16* o, int vb0, bf16x8 pa0, bf16x8 pa1, bf16x8 pa2, bf16x8 pa3, bool act) {
;     if (SK && !act) return;
;     ...
;     PV_D0(0); PV_D0(1); PV_D0(2); PV_D0(3);
	v_add_u32_e32 v239, 0x207b, v185
	v_cmp_gt_u32_e32 vcc, s62, v239
	v_add_u32_e32 v239, 0x5b, v185
	s_nop 0
	v_cndmask_b32_e32 v80, v235, v80, vcc
	v_cmp_lt_u32_e32 vcc, s65, v239
	v_add_u32_e32 v239, 0x7a, v185
	s_nop 0
	v_cndmask_b32_e32 v64, v235, v64, vcc
	v_cmp_lt_u32_e32 vcc, s65, v239
	v_add_u32_e32 v239, 0x5a, v185
	s_nop 0
	v_cndmask_b32_e32 v81, v235, v81, vcc
	v_cmp_lt_u32_e32 vcc, s65, v239
	v_add_u32_e32 v239, 0x79, v185
	s_nop 0
	v_cndmask_b32_e32 v65, v235, v65, vcc
	v_cmp_lt_u32_e32 vcc, s65, v239
	v_add_u32_e32 v239, 0x59, v185
	s_nop 0
	v_cndmask_b32_e32 v82, v235, v82, vcc
	v_cmp_lt_u32_e32 vcc, s65, v239
	v_add_u32_e32 v239, 0x78, v185
	s_nop 0
	v_cndmask_b32_e32 v66, v235, v66, vcc
	v_cmp_lt_u32_e32 vcc, s65, v239
	v_add_u32_e32 v239, 0x58, v185
	s_nop 0
	v_cndmask_b32_e32 v83, v235, v83, vcc
	v_cmp_lt_u32_e32 vcc, s65, v239
	v_add_u32_e32 v239, 0x73, v185
	s_nop 0
	v_cndmask_b32_e32 v67, v235, v67, vcc
	v_cmp_lt_u32_e32 vcc, s65, v239
	v_add_u32_e32 v239, 0x53, v185
	s_nop 0
	v_cndmask_b32_e32 v84, v235, v84, vcc
	v_cmp_lt_u32_e32 vcc, s65, v239
	v_add_u32_e32 v239, 0x72, v185
	s_nop 0
	v_cndmask_b32_e32 v68, v235, v68, vcc
	v_cmp_lt_u32_e32 vcc, s65, v239
	v_add_u32_e32 v239, 0x52, v185
	s_nop 0
	v_cndmask_b32_e32 v85, v235, v85, vcc
	v_cmp_lt_u32_e32 vcc, s65, v239
	v_add_u32_e32 v239, 0x71, v185
	s_nop 0
	v_cndmask_b32_e32 v69, v235, v69, vcc
	v_cmp_lt_u32_e32 vcc, s65, v239
	v_add_u32_e32 v239, 0x51, v185
	s_nop 0
	v_cndmask_b32_e32 v86, v235, v86, vcc
	v_cmp_lt_u32_e32 vcc, s65, v239
	v_add_u32_e32 v239, 0x70, v185
	s_nop 0
	v_cndmask_b32_e32 v70, v235, v70, vcc
	v_cmp_lt_u32_e32 vcc, s65, v239
	v_add_u32_e32 v239, 0x50, v185
	s_nop 0
	v_cndmask_b32_e32 v87, v235, v87, vcc
	v_cmp_lt_u32_e32 vcc, s65, v239
	v_add_u32_e32 v239, 0x6b, v185
	s_nop 0
	v_cndmask_b32_e32 v71, v235, v71, vcc
	v_cmp_lt_u32_e32 vcc, s65, v239
	v_add_u32_e32 v239, 0x4b, v185
	s_nop 0
	v_cndmask_b32_e32 v88, v235, v88, vcc
	v_cmp_lt_u32_e32 vcc, s65, v239
	v_add_u32_e32 v239, 0x6a, v185
	s_nop 0
	v_cndmask_b32_e32 v72, v235, v72, vcc
	v_cmp_lt_u32_e32 vcc, s65, v239
	v_add_u32_e32 v239, 0x4a, v185
	s_nop 0
	v_cndmask_b32_e32 v89, v235, v89, vcc
	v_cmp_lt_u32_e32 vcc, s65, v239
	v_add_u32_e32 v239, 0x69, v185
	s_nop 0
	v_cndmask_b32_e32 v73, v235, v73, vcc
	v_cmp_lt_u32_e32 vcc, s65, v239
	v_add_u32_e32 v239, 0x49, v185
	s_nop 0
	v_cndmask_b32_e32 v90, v235, v90, vcc
	v_cmp_lt_u32_e32 vcc, s65, v239
	v_add_u32_e32 v239, 0x68, v185
	s_nop 0
	v_cndmask_b32_e32 v74, v235, v74, vcc
	v_cmp_lt_u32_e32 vcc, s65, v239
	v_add_u32_e32 v239, 0x48, v185
	s_nop 0
	v_cndmask_b32_e32 v91, v235, v91, vcc
	v_cmp_lt_u32_e32 vcc, s65, v239
	v_add_u32_e32 v239, 0x63, v185
	s_nop 0
	v_cndmask_b32_e32 v75, v235, v75, vcc
	v_cmp_lt_u32_e32 vcc, s65, v239
	v_add_u32_e32 v239, 0x43, v185
	s_nop 0
	v_cndmask_b32_e32 v92, v235, v92, vcc
	v_cmp_lt_u32_e32 vcc, s65, v239
	v_add_u32_e32 v239, 0x62, v185
	s_nop 0
	v_cndmask_b32_e32 v76, v235, v76, vcc
	v_cmp_lt_u32_e32 vcc, s65, v239
	v_add_u32_e32 v239, 0x42, v185
	s_nop 0
	v_cndmask_b32_e32 v93, v235, v93, vcc
	v_cmp_lt_u32_e32 vcc, s65, v239
	v_add_u32_e32 v239, 0x61, v185
	s_nop 0
	v_cndmask_b32_e32 v77, v235, v77, vcc
	v_cmp_lt_u32_e32 vcc, s65, v239
	v_add_u32_e32 v239, 0x41, v185
	s_nop 0
	v_cndmask_b32_e32 v94, v235, v94, vcc
	v_cmp_lt_u32_e32 vcc, s65, v239
	v_add_u32_e32 v239, 0x60, v185
	s_nop 0
	v_cndmask_b32_e32 v78, v235, v78, vcc
	v_cmp_lt_u32_e32 vcc, s65, v239
	v_add_u32_e32 v239, 64, v185
	s_nop 0
	v_cndmask_b32_e32 v95, v235, v95, vcc
	v_cmp_lt_u32_e32 vcc, s65, v239
	s_nop 1
	v_cndmask_b32_e32 v79, v235, v79, vcc
.Lmy_h1_pv:
	ds_read_b64_tr_b16 v[224:225], v173 offset:0
	ds_read_b64_tr_b16 v[226:227], v173 offset:2048
	ds_read_b64_tr_b16 v[240:241], v173 offset:512
	ds_read_b64_tr_b16 v[242:243], v173 offset:2560
	ds_read_b64_tr_b16 v[244:245], v173 offset:1024
	ds_read_b64_tr_b16 v[246:247], v173 offset:3072
	ds_read_b64_tr_b16 v[248:249], v173 offset:1536
	ds_read_b64_tr_b16 v[250:251], v173 offset:3584
	v_max_f32_e32 v239, v81, v81
	v_max_f32_e32 v252, v80, v80
	v_max_f32_e32 v239, v252, v239
	s_waitcnt lgkmcnt(6)
	v_mfma_f32_32x32x16_bf16 v[32:47], v[144:147], v[224:227], v[32:47]
	v_max3_f32 v239, v239, v82, v83
	v_max3_f32 v239, v239, v84, v85
	ds_read_b64_tr_b16 v[224:225], v173 offset:4096
	ds_read_b64_tr_b16 v[226:227], v173 offset:6144
	v_max3_f32 v239, v239, v86, v87
	v_max3_f32 v239, v239, v88, v89
	v_max3_f32 v239, v239, v90, v91
	s_waitcnt lgkmcnt(6)
	v_mfma_f32_32x32x16_bf16 v[48:63], v[144:147], v[240:243], v[48:63]
	v_max3_f32 v239, v239, v92, v93
	v_max3_f32 v239, v239, v94, v95
	ds_read_b64_tr_b16 v[240:241], v173 offset:4608
	ds_read_b64_tr_b16 v[242:243], v173 offset:6656
	v_max3_f32 v239, v239, v64, v65
	v_max3_f32 v239, v239, v66, v67
	v_max3_f32 v239, v239, v68, v69
	s_waitcnt lgkmcnt(6)
	v_mfma_f32_32x32x16_bf16 v[16:31], v[144:147], v[244:247], v[16:31]
	v_max3_f32 v239, v239, v70, v71
	v_max3_f32 v239, v239, v72, v73
	ds_read_b64_tr_b16 v[244:245], v173 offset:5120
	ds_read_b64_tr_b16 v[246:247], v173 offset:7168
	v_max3_f32 v239, v239, v74, v75
	v_max3_f32 v239, v239, v76, v77
	v_max3_f32 v239, v239, v78, v79
	s_waitcnt lgkmcnt(6)
	v_mfma_f32_32x32x16_bf16 v[0:15], v[144:147], v[248:251], v[0:15]
	v_mov_b32_e32 v252, v239
	s_nop 1
	ds_read_b64_tr_b16 v[248:249], v173 offset:5632
	ds_read_b64_tr_b16 v[250:251], v173 offset:7680
	v_permlane32_swap_b32_e32 v239, v252
	v_max_f32_e32 v252, v252, v252
	v_max_f32_e32 v239, v239, v239
	s_waitcnt lgkmcnt(6)
; template <int VB, bool SK>
; __device__ __forceinline__ void pv_tile(f32x16* o, int vb0, bf16x8 pa0, bf16x8 pa1, bf16x8 pa2, bf16x8 pa3, bool act) {
;     if (SK && !act) return;
;     ...
;     PV_D0(0); PV_D0(1); PV_D0(2); PV_D0(3);
	v_mfma_f32_32x32x16_bf16 v[32:47], v[148:151], v[224:227], v[32:47]
	v_max_f32_e32 v239, v239, v252
	v_sub_f32_e32 v252, v239, v184
	ds_read_b64_tr_b16 v[224:225], v173 offset:8192
	ds_read_b64_tr_b16 v[226:227], v173 offset:10240
	v_mul_f32_e32 v252, 0x3db504f3, v252
	v_cmp_ge_f32_e32 vcc, s66, v252
	v_max_f32_e32 v252, v184, v184
	s_waitcnt lgkmcnt(6)
	v_mfma_f32_32x32x16_bf16 v[48:63], v[148:151], v[240:243], v[48:63]
	v_max_f32_e32 v239, v252, v239
	v_sub_f32_e32 v252, v184, v239
	ds_read_b64_tr_b16 v[240:241], v173 offset:8704
	ds_read_b64_tr_b16 v[242:243], v173 offset:10752
	v_mul_f32_e32 v252, 0x3e0293ee, v252
	v_exp_f32_e32 v252, v252
	s_cmp_eq_u64 vcc, exec
	s_waitcnt lgkmcnt(6)
	v_mfma_f32_32x32x16_bf16 v[16:31], v[148:151], v[244:247], v[16:31]
	s_cselect_b64 s[42:43], -1, 0
	v_cndmask_b32_e64 v184, v239, v184, s[42:43]
	ds_read_b64_tr_b16 v[244:245], v173 offset:9216
	ds_read_b64_tr_b16 v[246:247], v173 offset:11264
	v_mul_f32_e32 v228, 0xbe0293ee, v184
	v_fmamk_f32 v80, v80, 0x3e0293ee, v228
	v_fmamk_f32 v81, v81, 0x3e0293ee, v228
	s_waitcnt lgkmcnt(6)
	v_mfma_f32_32x32x16_bf16 v[0:15], v[148:151], v[248:251], v[0:15]
	v_fmamk_f32 v82, v82, 0x3e0293ee, v228
	v_fmamk_f32 v83, v83, 0x3e0293ee, v228
	ds_read_b64_tr_b16 v[248:249], v173 offset:9728
	ds_read_b64_tr_b16 v[250:251], v173 offset:11776
	v_fmamk_f32 v84, v84, 0x3e0293ee, v228
	v_fmamk_f32 v85, v85, 0x3e0293ee, v228
	v_fmamk_f32 v86, v86, 0x3e0293ee, v228
	s_waitcnt lgkmcnt(6)
	v_mfma_f32_32x32x16_bf16 v[32:47], v[152:155], v[224:227], v[32:47]
	v_fmamk_f32 v87, v87, 0x3e0293ee, v228
	v_fmamk_f32 v88, v88, 0x3e0293ee, v228
	ds_read_b64_tr_b16 v[224:225], v173 offset:12288
	ds_read_b64_tr_b16 v[226:227], v173 offset:14336
	v_fmamk_f32 v89, v89, 0x3e0293ee, v228
	v_fmamk_f32 v90, v90, 0x3e0293ee, v228
	v_fmamk_f32 v91, v91, 0x3e0293ee, v228
	s_waitcnt lgkmcnt(6)
	v_mfma_f32_32x32x16_bf16 v[48:63], v[152:155], v[240:243], v[48:63]
	v_fmamk_f32 v92, v92, 0x3e0293ee, v228
	v_fmamk_f32 v93, v93, 0x3e0293ee, v228
	ds_read_b64_tr_b16 v[240:241], v173 offset:12800
	ds_read_b64_tr_b16 v[242:243], v173 offset:14848
	v_fmamk_f32 v94, v94, 0x3e0293ee, v228
	v_fmamk_f32 v95, v95, 0x3e0293ee, v228
	v_exp_f32_e32 v144, v80
	s_waitcnt lgkmcnt(6)
	v_mfma_f32_32x32x16_bf16 v[16:31], v[152:155], v[244:247], v[16:31]
	v_exp_f32_e32 v145, v81
	v_exp_f32_e32 v146, v82
	ds_read_b64_tr_b16 v[244:245], v173 offset:13312
	ds_read_b64_tr_b16 v[246:247], v173 offset:15360
	v_exp_f32_e32 v147, v86
	v_fmamk_f32 v199, v64, 0x3e0293ee, v228
	v_fmamk_f32 v210, v65, 0x3e0293ee, v228
	s_waitcnt lgkmcnt(6)
	v_mfma_f32_32x32x16_bf16 v[0:15], v[152:155], v[248:251], v[0:15]
	v_fmamk_f32 v211, v66, 0x3e0293ee, v228
	v_fmamk_f32 v212, v67, 0x3e0293ee, v228
	ds_read_b64_tr_b16 v[248:249], v173 offset:13824
	ds_read_b64_tr_b16 v[250:251], v173 offset:15872
	v_exp_f32_e32 v148, v88
	v_exp_f32_e32 v149, v89
	v_exp_f32_e32 v150, v92
	s_waitcnt lgkmcnt(6)
	v_mfma_f32_32x32x16_bf16 v[32:47], v[156:159], v[224:227], v[32:47]
	v_exp_f32_e32 v151, v93
	v_fmamk_f32 v213, v68, 0x3e0293ee, v228
	v_fmamk_f32 v192, v69, 0x3e0293ee, v228
	v_fmamk_f32 v193, v70, 0x3e0293ee, v228
	v_fmamk_f32 v194, v71, 0x3e0293ee, v228
	s_waitcnt lgkmcnt(4)
	v_mfma_f32_32x32x16_bf16 v[48:63], v[156:159], v[240:243], v[48:63]
	v_fmamk_f32 v195, v72, 0x3e0293ee, v228
	v_fmamk_f32 v196, v73, 0x3e0293ee, v228
	v_exp_f32_e32 v152, v94
	v_exp_f32_e32 v153, v95
	v_exp_f32_e32 v154, v90
	s_waitcnt lgkmcnt(2)
	v_mfma_f32_32x32x16_bf16 v[16:31], v[156:159], v[244:247], v[16:31]
	v_exp_f32_e32 v155, v91
	v_fmamk_f32 v197, v74, 0x3e0293ee, v228
	v_fmamk_f32 v198, v75, 0x3e0293ee, v228
	v_fmamk_f32 v191, v76, 0x3e0293ee, v228
	v_fmamk_f32 v214, v77, 0x3e0293ee, v228
	s_waitcnt lgkmcnt(0)
	v_mfma_f32_32x32x16_bf16 v[0:15], v[156:159], v[248:251], v[0:15]
	v_fmamk_f32 v215, v78, 0x3e0293ee, v228
	v_fmamk_f32 v190, v79, 0x3e0293ee, v228
	v_exp_f32_e32 v156, v87
	v_exp_f32_e32 v157, v83
	v_exp_f32_e32 v158, v84
	v_exp_f32_e32 v159, v85
	s_waitcnt vmcnt(2)
	ds_write_b128 v176, v[136:139] offset:32768
	ds_write_b128 v176, v[140:143] offset:40960
	s_add_i32 s82, s74, 0x41
	s_lshl_b32 s82, s82, 8
	s_add_u32 s78, s98, s82
	s_addc_u32 s79, s99, 0
	s_add_u32 s80, s78, 0x2000
	s_addc_u32 s81, s79, 0
	v_lshl_add_u32 v240, v160, 8, v200
	global_load_dwordx4 v[136:139], v240, s[78:79]
	global_load_dwordx4 v[140:143], v240, s[80:81]
	s_waitcnt lgkmcnt(0)
	s_barrier
	v_cndmask_b32_e64 v189, v252, 1.0, s[42:43]
	v_cmp_gt_f32_e32 vcc, 1.0, v189
	s_waitcnt vmcnt(2)
	ds_write_b128 v181, v[128:131]
	ds_write_b128 v182, v[132:135]
	s_cbranch_vccz .LBB0_211
	s_and_saveexec_b64 s[8:9], s[40:41]
	ds_write_b32 v175, v189 offset:128
	s_or_b64 exec, exec, s[8:9]
	s_waitcnt lgkmcnt(0)
	ds_read_b128 v[128:131], v174 offset:224
	ds_read_b128 v[132:135], v174 offset:192
	ds_read_b128 v[80:83], v174 offset:160
	ds_read_b128 v[84:87], v174 offset:128
	s_waitcnt lgkmcnt(3)
	v_pk_mul_f32 v[46:47], v[46:47], v[130:131]
	s_waitcnt lgkmcnt(2)
	v_pk_mul_f32 v[42:43], v[42:43], v[134:135]
	s_waitcnt lgkmcnt(1)
	v_pk_mul_f32 v[38:39], v[38:39], v[82:83]
	s_waitcnt lgkmcnt(0)
	v_pk_mul_f32 v[34:35], v[34:35], v[86:87]
	v_pk_mul_f32 v[44:45], v[44:45], v[128:129]
	v_pk_mul_f32 v[40:41], v[40:41], v[132:133]
	v_pk_mul_f32 v[36:37], v[36:37], v[80:81]
	v_pk_mul_f32 v[32:33], v[32:33], v[84:85]
	v_pk_mul_f32 v[62:63], v[62:63], v[130:131]
	v_pk_mul_f32 v[58:59], v[58:59], v[134:135]
	v_pk_mul_f32 v[54:55], v[54:55], v[82:83]
	v_pk_mul_f32 v[50:51], v[50:51], v[86:87]
	v_pk_mul_f32 v[60:61], v[60:61], v[128:129]
	v_pk_mul_f32 v[56:57], v[56:57], v[132:133]
	v_pk_mul_f32 v[52:53], v[52:53], v[80:81]
	v_pk_mul_f32 v[48:49], v[48:49], v[84:85]
	v_pk_mul_f32 v[30:31], v[30:31], v[130:131]
	v_pk_mul_f32 v[26:27], v[26:27], v[134:135]
	v_pk_mul_f32 v[22:23], v[22:23], v[82:83]
	v_pk_mul_f32 v[18:19], v[18:19], v[86:87]
	v_pk_mul_f32 v[28:29], v[28:29], v[128:129]
	v_pk_mul_f32 v[24:25], v[24:25], v[132:133]
	v_pk_mul_f32 v[20:21], v[20:21], v[80:81]
	v_pk_mul_f32 v[16:17], v[16:17], v[84:85]
	v_pk_mul_f32 v[14:15], v[14:15], v[130:131]
	v_pk_mul_f32 v[10:11], v[10:11], v[134:135]
	v_pk_mul_f32 v[6:7], v[6:7], v[82:83]
	v_pk_mul_f32 v[2:3], v[2:3], v[86:87]
	v_pk_mul_f32 v[12:13], v[12:13], v[128:129]
	v_pk_mul_f32 v[8:9], v[8:9], v[132:133]
	v_pk_mul_f32 v[4:5], v[4:5], v[80:81]
	v_pk_mul_f32 v[0:1], v[0:1], v[84:85]
; template <int KB, bool SK>
; __device__ __forceinline__ void qkt(f32x16& p0, f32x16& p1, const char* K_lds, int r32, int hi, const bf16x8* qr, bool act) {
;     if (SK && !act) { const float NEG = -__builtin_inff();
; #pragma unroll
;         for (int r = 0; r < 16; ++r) { p0[r] = NEG; p1[r] = NEG; } return; }
;     p0 = f32x16{}; p1 = f32x16{};
;     const char* kb[4];
; #pragma unroll
;     for (int dd = 0; dd < 4; ++dd) kb[dd] = K_lds + KB * SHM_K + KSWZ(r32, (dd * 16 + hi * 8) * 2);
; #pragma unroll
;     for (int d0 = 0; d0 < 8; ++d0) { const char* a = kb[d0 & 3] + (d0 >> 2) * 128;
;         bf16x8 b0 = *reinterpret_cast<const bf16x8*>(a);
;         bf16x8 b1 = *reinterpret_cast<const bf16x8*>(a + 32 * 256);
;         p0 = __builtin_amdgcn_mfma_f32_32x32x16_bf16(b0, qr[d0], p0, 0, 0, 0);
;         p1 = __builtin_amdgcn_mfma_f32_32x32x16_bf16(b1, qr[d0], p1, 0, 0, 0); }
; }
.LBB0_211:
	s_waitcnt lgkmcnt(0)
	s_add_i32 s42, s73, 1
	s_cmp_lt_u32 s42, s71
	s_cselect_b64 s[8:9], -1, 0
	s_add_i32 s82, s74, 0x41
	s_lshl_b32 s82, s82, 8
	s_add_u32 s78, s100, s82
	s_addc_u32 s79, s101, 0
	s_add_u32 s80, s78, 0x2000
	s_addc_u32 s81, s79, 0
	v_lshl_add_u32 v240, v160, 8, v200
	global_load_dwordx4 v[128:131], v240, s[78:79]
	global_load_dwordx4 v[132:135], v240, s[80:81]
	ds_read_b128 v[64:67], v180 offset:32768
	ds_read_b128 v[68:71], v180 offset:40960
	ds_read_b128 v[216:219], v179 offset:32768
	ds_read_b128 v[220:223], v179 offset:40960
	ds_read_b128 v[224:227], v165 offset:32768
	ds_read_b128 v[248:251], v165 offset:40960
	v_exp_f32_e32 v199, v199
	v_exp_f32_e32 v210, v210
	v_exp_f32_e32 v211, v211
	v_exp_f32_e32 v212, v212
	v_exp_f32_e32 v213, v213
	v_exp_f32_e32 v192, v192
	s_waitcnt lgkmcnt(5)
	v_mfma_f32_32x32x16_bf16 v[80:95], v[64:67], v[124:127], 0
	v_exp_f32_e32 v193, v193
	v_exp_f32_e32 v194, v194
	v_exp_f32_e32 v195, v195
	s_waitcnt lgkmcnt(4)
	v_mfma_f32_32x32x16_bf16 v[64:79], v[68:71], v[124:127], 0
	v_exp_f32_e32 v196, v196
	v_exp_f32_e32 v197, v197
	v_exp_f32_e32 v198, v198
	v_exp_f32_e32 v191, v191
	v_exp_f32_e32 v214, v214
	v_exp_f32_e32 v215, v215
	s_waitcnt lgkmcnt(3)
	v_mfma_f32_32x32x16_bf16 v[80:95], v[216:219], v[120:123], v[80:95]
	v_exp_f32_e32 v190, v190
	v_add_f32_e32 v239, 0, v144
	v_add_f32_e32 v239, v145, v239
	s_waitcnt lgkmcnt(2)
	v_mfma_f32_32x32x16_bf16 v[64:79], v[220:223], v[120:123], v[64:79]
	ds_read_b128 v[216:219], v163 offset:32768
	ds_read_b128 v[220:223], v163 offset:40960
	v_add_f32_e32 v239, v146, v239
	v_add_f32_e32 v239, v157, v239
	v_add_f32_e32 v239, v158, v239
	v_add_f32_e32 v239, v159, v239
	v_add_f32_e32 v239, v147, v239
	v_add_f32_e32 v239, v156, v239
	s_waitcnt lgkmcnt(3)
	v_mfma_f32_32x32x16_bf16 v[80:95], v[224:227], v[116:119], v[80:95]
	v_add_f32_e32 v239, v148, v239
	v_add_f32_e32 v239, v149, v239
	v_add_f32_e32 v239, v154, v239
	s_waitcnt lgkmcnt(2)
	v_mfma_f32_32x32x16_bf16 v[64:79], v[248:251], v[116:119], v[64:79]
	ds_read_b128 v[224:227], v180 offset:32896
	ds_read_b128 v[248:251], v180 offset:41088
	v_add_f32_e32 v239, v155, v239
	v_add_f32_e32 v239, v150, v239
	v_add_f32_e32 v239, v151, v239
	v_add_f32_e32 v239, v152, v239
	v_add_f32_e32 v239, v153, v239
	v_add_f32_e32 v239, v199, v239
	s_waitcnt lgkmcnt(3)
	v_mfma_f32_32x32x16_bf16 v[80:95], v[216:219], v[112:115], v[80:95]
	v_add_f32_e32 v239, v210, v239
	v_add_f32_e32 v239, v211, v239
	v_add_f32_e32 v239, v212, v239
	s_waitcnt lgkmcnt(2)
	v_mfma_f32_32x32x16_bf16 v[64:79], v[220:223], v[112:115], v[64:79]
	ds_read_b128 v[216:219], v179 offset:32896
	ds_read_b128 v[220:223], v179 offset:41088
	v_add_f32_e32 v239, v213, v239
	v_add_f32_e32 v239, v192, v239
	v_add_f32_e32 v239, v193, v239
	v_add_f32_e32 v239, v194, v239
	v_add_f32_e32 v239, v195, v239
	v_add_f32_e32 v239, v196, v239
	s_waitcnt lgkmcnt(3)
	v_mfma_f32_32x32x16_bf16 v[80:95], v[224:227], v[108:111], v[80:95]
	v_add_f32_e32 v239, v197, v239
	v_add_f32_e32 v239, v198, v239
	v_add_f32_e32 v239, v191, v239
	s_waitcnt lgkmcnt(2)
	v_mfma_f32_32x32x16_bf16 v[64:79], v[248:251], v[108:111], v[64:79]
	ds_read_b128 v[224:227], v165 offset:32896
	ds_read_b128 v[248:251], v165 offset:41088
	v_add_f32_e32 v239, v214, v239
	v_add_f32_e32 v239, v215, v239
	v_cvt_pk_bf16_f32 v144, v144, v145
	v_cvt_pk_bf16_f32 v145, v146, v157
	v_cvt_pk_bf16_f32 v146, v158, v159
	v_cvt_pk_bf16_f32 v147, v147, v156
	s_waitcnt lgkmcnt(3)
	v_mfma_f32_32x32x16_bf16 v[80:95], v[216:219], v[104:107], v[80:95]
	v_cvt_pk_bf16_f32 v148, v148, v149
	v_cvt_pk_bf16_f32 v149, v154, v155
	v_cvt_pk_bf16_f32 v150, v150, v151
	s_waitcnt lgkmcnt(2)
	v_mfma_f32_32x32x16_bf16 v[64:79], v[220:223], v[104:107], v[64:79]
	ds_read_b128 v[216:219], v163 offset:32896
	ds_read_b128 v[220:223], v163 offset:41088
	v_cvt_pk_bf16_f32 v151, v152, v153
	v_cvt_pk_bf16_f32 v152, v199, v210
	v_cvt_pk_bf16_f32 v153, v211, v212
	v_cvt_pk_bf16_f32 v154, v213, v192
	v_cvt_pk_bf16_f32 v155, v193, v194
	v_cvt_pk_bf16_f32 v156, v195, v196
	s_waitcnt lgkmcnt(3)
	v_mfma_f32_32x32x16_bf16 v[80:95], v[224:227], v[100:103], v[80:95]
	v_cvt_pk_bf16_f32 v157, v197, v198
	v_cvt_pk_bf16_f32 v158, v191, v214
	v_cvt_pk_bf16_f32 v159, v215, v190
	s_waitcnt lgkmcnt(2)
	v_mfma_f32_32x32x16_bf16 v[64:79], v[248:251], v[100:103], v[64:79]
	v_permlane32_swap_b32_e32 v144, v146
	v_permlane32_swap_b32_e32 v145, v147
	v_permlane32_swap_b32_e32 v148, v150
	v_permlane32_swap_b32_e32 v149, v151
	v_permlane32_swap_b32_e32 v152, v154
	v_permlane32_swap_b32_e32 v153, v155
	s_waitcnt lgkmcnt(1)
	v_mfma_f32_32x32x16_bf16 v[80:95], v[216:219], v[96:99], v[80:95]
	v_add_f32_e32 v216, v190, v239
	v_mov_b32_e32 v217, v216
	v_permlane32_swap_b32_e32 v156, v158
	v_permlane32_swap_b32_e32 v157, v159
	s_waitcnt lgkmcnt(0)
	v_mfma_f32_32x32x16_bf16 v[64:79], v[220:223], v[96:99], v[64:79]
	s_nop 1
	v_permlane32_swap_b32_e32 v216, v217

; __device__ __forceinline__ void partialSM(f32x16& p0, f32x16& p1, float& m_reg, float& mn, float& alpha) {
;     float pmax = p0[0]; for (int r = 1; r < 16; ++r) pmax = fmaxf(pmax, p0[r]); for (int r = 0; r < 16; ++r) pmax = fmaxf(pmax, p1[r]);
;     { auto rr = __builtin_amdgcn_permlane32_swap(__float_as_uint(pmax), __float_as_uint(pmax), false, false);
;       pmax = fmaxf(__uint_as_float(rr[0]), __uint_as_float(rr[1])); }
;     constexpr float C2 = 1.4426950408889634f * SCALE;
;     if (__builtin_expect(__all((pmax - m_reg) * SCALE <= THR), 1)) { mn = m_reg; alpha = 1.f; }
;     else { mn = fmaxf(m_reg, pmax); alpha = __builtin_amdgcn_exp2f((m_reg - mn) * C2); m_reg = mn; }
;     const float mnL = -mn * C2;
;     for (int r = 0; r < 16; ++r) p0[r] = fmaf(p0[r], C2, mnL); for (int r = 0; r < 16; ++r) p1[r] = fmaf(p1[r], C2, mnL);
;     for (int r = 0; r < 16; ++r) p0[r] = __builtin_amdgcn_exp2f(p0[r]);
; }
; template <int VB, bool SK>
; __device__ __forceinline__ void pv_tile(f32x16* o, int vb0, bf16x8 pa0, bf16x8 pa1, bf16x8 pa2, bf16x8 pa3, bool act) {
;     if (SK && !act) return;
;     ...
;     PV_D0(0); PV_D0(1); PV_D0(2); PV_D0(3);
.Lmy_h2_pv:
	ds_read_b64_tr_b16 v[224:225], v173 offset:16384
	ds_read_b64_tr_b16 v[226:227], v173 offset:18432
	ds_read_b64_tr_b16 v[240:241], v173 offset:16896
	ds_read_b64_tr_b16 v[242:243], v173 offset:18944
	ds_read_b64_tr_b16 v[244:245], v173 offset:17408
	ds_read_b64_tr_b16 v[246:247], v173 offset:19456
	ds_read_b64_tr_b16 v[248:249], v173 offset:17920
	ds_read_b64_tr_b16 v[250:251], v173 offset:19968
	v_max_f32_e32 v239, v81, v81
	v_max_f32_e32 v252, v80, v80
	v_max_f32_e32 v239, v252, v239
	s_waitcnt lgkmcnt(6)
	v_mfma_f32_32x32x16_bf16 v[32:47], v[144:147], v[224:227], v[32:47]
	v_max3_f32 v239, v239, v82, v83
	v_max3_f32 v239, v239, v84, v85
	ds_read_b64_tr_b16 v[224:225], v173 offset:20480
	ds_read_b64_tr_b16 v[226:227], v173 offset:22528
	v_max3_f32 v239, v239, v86, v87
	v_max3_f32 v239, v239, v88, v89
	v_max3_f32 v239, v239, v90, v91
	s_waitcnt lgkmcnt(6)
	v_mfma_f32_32x32x16_bf16 v[48:63], v[144:147], v[240:243], v[48:63]
	v_max3_f32 v239, v239, v92, v93
	v_max3_f32 v239, v239, v94, v95
	ds_read_b64_tr_b16 v[240:241], v173 offset:20992
	ds_read_b64_tr_b16 v[242:243], v173 offset:23040
	v_max3_f32 v239, v239, v64, v65
	v_max3_f32 v239, v239, v66, v67
	v_max3_f32 v239, v239, v68, v69
	s_waitcnt lgkmcnt(6)
	v_mfma_f32_32x32x16_bf16 v[16:31], v[144:147], v[244:247], v[16:31]
	v_max3_f32 v239, v239, v70, v71
	v_max3_f32 v239, v239, v72, v73
	ds_read_b64_tr_b16 v[244:245], v173 offset:21504
	ds_read_b64_tr_b16 v[246:247], v173 offset:23552
	v_max3_f32 v239, v239, v74, v75
	v_max3_f32 v239, v239, v76, v77
	v_max3_f32 v239, v239, v78, v79
	s_waitcnt lgkmcnt(6)
	v_mfma_f32_32x32x16_bf16 v[0:15], v[144:147], v[248:251], v[0:15]
	v_mov_b32_e32 v252, v239
	s_nop 1
	ds_read_b64_tr_b16 v[248:249], v173 offset:22016
	ds_read_b64_tr_b16 v[250:251], v173 offset:24064
	v_permlane32_swap_b32_e32 v239, v252
	v_max_f32_e32 v252, v252, v252
	v_max_f32_e32 v239, v239, v239
	s_waitcnt lgkmcnt(6)
	v_mfma_f32_32x32x16_bf16 v[32:47], v[148:151], v[224:227], v[32:47]
	v_max_f32_e32 v239, v239, v252
	v_sub_f32_e32 v252, v239, v184
	ds_read_b64_tr_b16 v[224:225], v173 offset:24576
	ds_read_b64_tr_b16 v[226:227], v173 offset:26624
	v_mul_f32_e32 v252, 0x3db504f3, v252
	v_cmp_ge_f32_e32 vcc, s66, v252
	s_cmp_eq_u64 vcc, exec
	s_waitcnt lgkmcnt(6)
	v_mfma_f32_32x32x16_bf16 v[48:63], v[148:151], v[240:243], v[48:63]
	s_cselect_b64 s[42:43], -1, 0
	v_max_f32_e32 v253, v184, v184
	ds_read_b64_tr_b16 v[240:241], v173 offset:25088
	ds_read_b64_tr_b16 v[242:243], v173 offset:27136
	v_max_f32_e32 v253, v253, v239
	v_sub_f32_e32 v252, v184, v253
	v_mul_f32_e32 v252, 0x3e0293ee, v252
	s_waitcnt lgkmcnt(6)
	v_mfma_f32_32x32x16_bf16 v[16:31], v[148:151], v[244:247], v[16:31]
	v_exp_f32_e32 v252, v252
	s_nop 0
	ds_read_b64_tr_b16 v[244:245], v173 offset:25600
	ds_read_b64_tr_b16 v[246:247], v173 offset:27648
	v_cndmask_b32_e64 v188, v252, 1.0, s[42:43]
	v_cndmask_b32_e64 v184, v253, v184, s[42:43]
	v_mul_f32_e32 v228, 0xbe0293ee, v184
	s_waitcnt lgkmcnt(6)
	v_mfma_f32_32x32x16_bf16 v[0:15], v[148:151], v[248:251], v[0:15]
	v_mov_b32_e32 v229, v228
	v_fmamk_f32 v80, v80, 0x3e0293ee, v228
	ds_read_b64_tr_b16 v[248:249], v173 offset:26112
	ds_read_b64_tr_b16 v[250:251], v173 offset:28160
	v_fmamk_f32 v81, v81, 0x3e0293ee, v228
	v_fmamk_f32 v82, v82, 0x3e0293ee, v228
	v_fmamk_f32 v83, v83, 0x3e0293ee, v228
	s_waitcnt lgkmcnt(6)
	v_mfma_f32_32x32x16_bf16 v[32:47], v[152:155], v[224:227], v[32:47]
	v_fmamk_f32 v84, v84, 0x3e0293ee, v228
	v_fmamk_f32 v85, v85, 0x3e0293ee, v228
	ds_read_b64_tr_b16 v[224:225], v173 offset:28672
	ds_read_b64_tr_b16 v[226:227], v173 offset:30720
	v_fmamk_f32 v86, v86, 0x3e0293ee, v228
	v_fmamk_f32 v87, v87, 0x3e0293ee, v228
	v_fmamk_f32 v88, v88, 0x3e0293ee, v228
	s_waitcnt lgkmcnt(6)
	v_mfma_f32_32x32x16_bf16 v[48:63], v[152:155], v[240:243], v[48:63]
	v_fmamk_f32 v89, v89, 0x3e0293ee, v228
	v_fmamk_f32 v90, v90, 0x3e0293ee, v228
	ds_read_b64_tr_b16 v[240:241], v173 offset:29184
	ds_read_b64_tr_b16 v[242:243], v173 offset:31232
	v_fmamk_f32 v91, v91, 0x3e0293ee, v228
	v_fmamk_f32 v92, v92, 0x3e0293ee, v228
	v_fmamk_f32 v93, v93, 0x3e0293ee, v228
	s_waitcnt lgkmcnt(6)
	v_mfma_f32_32x32x16_bf16 v[16:31], v[152:155], v[244:247], v[16:31]
	v_fmamk_f32 v94, v94, 0x3e0293ee, v228
	v_fmac_f32_e32 v229, 0x3e0293ee, v95
	ds_read_b64_tr_b16 v[244:245], v173 offset:29696
	ds_read_b64_tr_b16 v[246:247], v173 offset:31744
	v_exp_f32_e32 v198, v80
	v_exp_f32_e32 v199, v81
	v_exp_f32_e32 v210, v82
	s_waitcnt lgkmcnt(6)
	v_mfma_f32_32x32x16_bf16 v[0:15], v[152:155], v[248:251], v[0:15]
	v_exp_f32_e32 v212, v83
	v_exp_f32_e32 v213, v84
	ds_read_b64_tr_b16 v[248:249], v173 offset:30208
	ds_read_b64_tr_b16 v[250:251], v173 offset:32256
	v_exp_f32_e32 v215, v85
	v_exp_f32_e32 v211, v86
	v_exp_f32_e32 v214, v87
	s_waitcnt lgkmcnt(6)
	v_mfma_f32_32x32x16_bf16 v[32:47], v[156:159], v[224:227], v[32:47]
	v_exp_f32_e32 v190, v88
	v_exp_f32_e32 v192, v89
	v_exp_f32_e32 v193, v90
	v_exp_f32_e32 v196, v91
	v_exp_f32_e32 v191, v92
	s_waitcnt lgkmcnt(4)
	v_mfma_f32_32x32x16_bf16 v[48:63], v[156:159], v[240:243], v[48:63]
	v_exp_f32_e32 v194, v93
	v_exp_f32_e32 v195, v94
	v_exp_f32_e32 v197, v229
	v_fmamk_f32 v144, v72, 0x3e0293ee, v228
	v_fmamk_f32 v145, v73, 0x3e0293ee, v228
	s_waitcnt lgkmcnt(2)
	v_mfma_f32_32x32x16_bf16 v[16:31], v[156:159], v[244:247], v[16:31]
	v_fmamk_f32 v146, v78, 0x3e0293ee, v228
	v_fmamk_f32 v147, v79, 0x3e0293ee, v228
	v_fmamk_f32 v148, v70, 0x3e0293ee, v228
	v_fmamk_f32 v149, v71, 0x3e0293ee, v228
	v_fmamk_f32 v150, v68, 0x3e0293ee, v228
	s_waitcnt lgkmcnt(0)
	v_mfma_f32_32x32x16_bf16 v[0:15], v[156:159], v[248:251], v[0:15]
	v_fmamk_f32 v151, v69, 0x3e0293ee, v228
	v_fmamk_f32 v152, v76, 0x3e0293ee, v228
	v_fmamk_f32 v153, v77, 0x3e0293ee, v228
	v_fmamk_f32 v154, v66, 0x3e0293ee, v228
	v_fmamk_f32 v155, v67, 0x3e0293ee, v228
	v_fmamk_f32 v156, v64, 0x3e0293ee, v228
	v_fmamk_f32 v157, v65, 0x3e0293ee, v228
	v_fmamk_f32 v158, v74, 0x3e0293ee, v228
	v_fmamk_f32 v159, v75, 0x3e0293ee, v228
	s_waitcnt vmcnt(2)
	s_andn2_b64 vcc, exec, s[8:9]
	s_cbranch_vccnz .Lmy_h2_skipk
	ds_write_b128 v176, v[136:139] offset:49152
	ds_write_b128 v176, v[140:143] offset:57344
; template <class TIn, class TOut>
; __device__ __forceinline__ void causal_swa_block(const BlockRef<TIn, TOut>& cur, const BlockRef<TIn, TOut>& nxt, int skv, int W, char* lds, Seam<TIn>& S) {
;     ...
;     for (int t = 1; t + 1 < NT; t += 2) {
;         HALF_STEP(pB0, pB1, mnB, alB, pA0, pA1, alA, t, 1, 0, 0);
;         HALF_STEP(pA0, pA1, mnA, alA, pB0, pB1, alB, t + 1, 0, 1, 1);
;     }
.Lmy_h2_skipk:
	s_add_i32 s82, s74, 0x81
	s_lshl_b32 s82, s82, 8
	s_add_u32 s78, s98, s82
	s_addc_u32 s79, s99, 0
	s_add_u32 s80, s78, 0x2000
	s_addc_u32 s81, s79, 0
	v_lshl_add_u32 v240, v160, 8, v200
	global_load_dwordx4 v[136:139], v240, s[78:79]
	global_load_dwordx4 v[140:143], v240, s[80:81]
	s_waitcnt lgkmcnt(0)
	s_barrier
	s_waitcnt vmcnt(2)
	s_andn2_b64 vcc, exec, s[8:9]
	s_cbranch_vccnz .LBB0_217
	ds_write_b128 v181, v[128:131] offset:16384
	ds_write_b128 v182, v[132:135] offset:16384
.LBB0_217:
	v_cmp_gt_f32_e32 vcc, 1.0, v188
	s_cbranch_vccz .LBB0_221
	s_and_saveexec_b64 s[8:9], s[40:41]
	ds_write_b32 v175, v188 offset:128
	s_or_b64 exec, exec, s[8:9]
	s_waitcnt lgkmcnt(0)
	s_waitcnt vmcnt(2)
	ds_read_b128 v[128:131], v174 offset:224
	s_waitcnt vmcnt(1)
	ds_read_b128 v[132:135], v174 offset:192
	s_waitcnt vmcnt(0)
	ds_read_b128 v[80:83], v174 offset:160
	ds_read_b128 v[84:87], v174 offset:128
	s_waitcnt lgkmcnt(3)
	v_pk_mul_f32 v[46:47], v[46:47], v[130:131]
	s_waitcnt lgkmcnt(2)
	v_pk_mul_f32 v[42:43], v[42:43], v[134:135]
	s_waitcnt lgkmcnt(1)
	v_pk_mul_f32 v[38:39], v[38:39], v[82:83]
	s_waitcnt lgkmcnt(0)
	v_pk_mul_f32 v[34:35], v[34:35], v[86:87]
	v_pk_mul_f32 v[44:45], v[44:45], v[128:129]
	v_pk_mul_f32 v[40:41], v[40:41], v[132:133]
	v_pk_mul_f32 v[36:37], v[36:37], v[80:81]
	v_pk_mul_f32 v[32:33], v[32:33], v[84:85]
	v_pk_mul_f32 v[62:63], v[62:63], v[130:131]
	v_pk_mul_f32 v[58:59], v[58:59], v[134:135]
	v_pk_mul_f32 v[54:55], v[54:55], v[82:83]
	v_pk_mul_f32 v[50:51], v[50:51], v[86:87]
	v_pk_mul_f32 v[60:61], v[60:61], v[128:129]
	v_pk_mul_f32 v[56:57], v[56:57], v[132:133]
	v_pk_mul_f32 v[52:53], v[52:53], v[80:81]
	v_pk_mul_f32 v[48:49], v[48:49], v[84:85]
	v_pk_mul_f32 v[30:31], v[30:31], v[130:131]
	v_pk_mul_f32 v[26:27], v[26:27], v[134:135]
	v_pk_mul_f32 v[22:23], v[22:23], v[82:83]
	v_pk_mul_f32 v[18:19], v[18:19], v[86:87]
	v_pk_mul_f32 v[28:29], v[28:29], v[128:129]
	v_pk_mul_f32 v[24:25], v[24:25], v[132:133]
	v_pk_mul_f32 v[20:21], v[20:21], v[80:81]
	v_pk_mul_f32 v[16:17], v[16:17], v[84:85]
	v_pk_mul_f32 v[14:15], v[14:15], v[130:131]
	v_pk_mul_f32 v[10:11], v[10:11], v[134:135]
	v_pk_mul_f32 v[6:7], v[6:7], v[82:83]
	v_pk_mul_f32 v[2:3], v[2:3], v[86:87]
	v_pk_mul_f32 v[12:13], v[12:13], v[128:129]
	v_pk_mul_f32 v[8:9], v[8:9], v[132:133]
	v_pk_mul_f32 v[4:5], v[4:5], v[80:81]
	v_pk_mul_f32 v[0:1], v[0:1], v[84:85]
.LBB0_221:
	v_add_f32_e32 v64, v186, v187
	v_fmac_f32_e32 v64, v183, v177
	v_add_f32_e32 v177, v216, v217
	s_addk_i32 s74, 0x80
	s_add_i32 s73, s73, 2
	v_fmac_f32_e32 v177, v64, v189
	s_cmp_lt_u32 s73, s71
	v_add_u32_e32 v185, 0xffffff80, v185
	s_waitcnt lgkmcnt(0)
	s_cbranch_scc1 .Lmy_cont
	s_waitcnt vmcnt(0)
	s_barrier
	s_branch .LBB0_223
